# one static priority raise at entry for waves 0-3 (no per-segment toggles)
# speedup vs baseline: 1.0162x; 1.0162x over previous
; #define LAS __attribute__((address_space(3)))
; __global__ void __launch_bounds__(NWAVES * 64, 2) fwd_kernel(Args a) {
;     extern __shared__ __attribute__((aligned(16))) unsigned char lds_raw[];
;     LAS unsigned char* lds = (LAS unsigned char*)lds_raw;
;     const int G = gridDim.x, cu = blockIdx.x;
;     const int lo = a.ph_lo, hi = a.ph_hi;
;     const bool spread = (G == 256) && MK_ONE;
;     ...
;     cg::grid_group grid = cg::this_grid();
;     { volatile LAS unsigned* misc = (volatile LAS unsigned*)(lds + MISC_OFF); if (threadIdx.x < 32) misc[threadIdx.x] = 0u; __syncthreads(); }
_Z10fwd_kernel4Args:
	s_load_dwordx4 s[68:71], s[0:1], 0xa8
	s_add_u32 s10, s0, 0xb0
	v_and_b32_e32 v210, 0x3ff, v0
	s_addc_u32 s11, s1, 0
	v_cmp_gt_u32_e32 vcc, 32, v210
	v_lshl_add_u32 v135, v210, 2, 0
	v_lshrrev_b32_e32 v1, 6, v210
	v_readfirstlane_b32 s4, v1
	s_nop 3
	s_cmp_lt_u32 s4, 4
	s_cbranch_scc0 .Lprio_keep
	s_setprio 1
